# t1 + in-proj epilogue rstd loads prefetched in the last K-iteration (latency hidden behind MFMA phases)
# baseline (speedup 1.0000x reference)
.LBB0_218:
	s_waitcnt lgkmcnt(0)
	ds_read_b128 v[150:153], v189
	ds_read_b128 v[154:157], v189 offset:1024
	ds_read_b128 v[162:165], v189 offset:2048
	ds_read_b128 v[166:169], v189 offset:3072
	ds_read_b128 v[170:173], v190
	ds_read_b128 v[174:177], v190 offset:1024
	ds_read_b128 v[178:181], v190 offset:2048
	ds_read_b128 v[182:185], v190 offset:3072
	s_add_u32 s8, s2, 0xfff80080
	s_addc_u32 s9, s3, -1
	s_cmp_eq_u32 s58, 28
	s_cselect_b32 s57, s1, s9
	s_cselect_b32 s56, s7, s8
	s_cselect_b32 s9, s33, s51
	s_cselect_b32 s8, s36, s49
	s_cbranch_scc0 .Lrstd_pf_skip
	v_lshl_add_u32 v242, s0, 8, v186
	v_ashrrev_i32_e32 v243, 31, v242
	v_lshl_add_u64 v[242:243], v[242:243], 2, s[66:67]
	global_load_dword v234, v[242:243], off
	global_load_dword v235, v[242:243], off offset:64
	global_load_dword v236, v[242:243], off offset:128
	global_load_dword v237, v[242:243], off offset:192
	global_load_dword v238, v[242:243], off offset:512
	global_load_dword v239, v[242:243], off offset:576
	global_load_dword v240, v[242:243], off offset:640
	global_load_dword v241, v[242:243], off offset:704
.Lrstd_pf_skip:
	v_lshl_add_u64 v[158:159], s[2:3], 0, v[142:143]
	s_add_i32 m0, s70, 0xc000
	ds_read_b128 v[194:197], v191
	ds_read_b128 v[198:201], v191 offset:1024
	ds_read_b128 v[202:205], v191 offset:2048
	ds_read_b128 v[206:209], v191 offset:3072
	ds_read_b128 v[210:213], v191 offset:4096
	ds_read_b128 v[214:217], v191 offset:5120
	ds_read_b128 v[218:221], v191 offset:6144
	ds_read_b128 v[222:225], v191 offset:7168
	global_load_lds_dwordx4 v[158:159], off
	v_lshl_add_u64 v[158:159], s[2:3], 0, v[144:145]
	s_add_i32 m0, s70, 0xe000
	s_nop 0
	global_load_lds_dwordx4 v[158:159], off
	s_cmp_eq_u32 s58, 28
	s_cbranch_scc1 .Lrstd_w0_last
	s_waitcnt vmcnt(8)
	s_branch .Lrstd_w0_done
.Lrstd_w0_last:
	s_waitcnt vmcnt(16)
.Lrstd_w0_done:
	s_waitcnt lgkmcnt(0)
	s_barrier
	s_setprio 1
	s_waitcnt lgkmcnt(0)
	v_mfma_f32_16x16x32_bf16 v[124:127], v[150:153], v[194:197], v[124:127]
	v_mfma_f32_16x16x32_bf16 v[120:123], v[162:165], v[194:197], v[120:123]
	v_mfma_f32_16x16x32_bf16 v[108:111], v[150:153], v[202:205], v[108:111]
	v_mfma_f32_16x16x32_bf16 v[104:107], v[162:165], v[202:205], v[104:107]
	v_mfma_f32_16x16x32_bf16 v[92:95], v[150:153], v[210:213], v[92:95]
	v_mfma_f32_16x16x32_bf16 v[88:91], v[162:165], v[210:213], v[88:91]
	v_mfma_f32_16x16x32_bf16 v[76:79], v[150:153], v[218:221], v[76:79]
	v_mfma_f32_16x16x32_bf16 v[72:75], v[162:165], v[218:221], v[72:75]
	v_mfma_f32_16x16x32_bf16 v[124:127], v[154:157], v[198:201], v[124:127]
	v_mfma_f32_16x16x32_bf16 v[120:123], v[166:169], v[198:201], v[120:123]
	v_mfma_f32_16x16x32_bf16 v[108:111], v[154:157], v[206:209], v[108:111]
	v_mfma_f32_16x16x32_bf16 v[104:107], v[166:169], v[206:209], v[104:107]
	v_mfma_f32_16x16x32_bf16 v[92:95], v[154:157], v[214:217], v[92:95]
	v_mfma_f32_16x16x32_bf16 v[88:91], v[166:169], v[214:217], v[88:91]
	v_mfma_f32_16x16x32_bf16 v[76:79], v[154:157], v[222:225], v[76:79]
	v_mfma_f32_16x16x32_bf16 v[72:75], v[166:169], v[222:225], v[72:75]
	s_setprio 0
	s_setprio 1
	v_mfma_f32_16x16x32_bf16 v[116:119], v[170:173], v[194:197], v[116:119]
	v_mfma_f32_16x16x32_bf16 v[112:115], v[178:181], v[194:197], v[112:115]
	v_mfma_f32_16x16x32_bf16 v[100:103], v[170:173], v[202:205], v[100:103]
	v_mfma_f32_16x16x32_bf16 v[96:99], v[178:181], v[202:205], v[96:99]
	v_mfma_f32_16x16x32_bf16 v[84:87], v[170:173], v[210:213], v[84:87]
	v_mfma_f32_16x16x32_bf16 v[80:83], v[178:181], v[210:213], v[80:83]
	v_mfma_f32_16x16x32_bf16 v[68:71], v[170:173], v[218:221], v[68:71]
	v_mfma_f32_16x16x32_bf16 v[64:67], v[178:181], v[218:221], v[64:67]
	v_mfma_f32_16x16x32_bf16 v[116:119], v[174:177], v[198:201], v[116:119]
	v_mfma_f32_16x16x32_bf16 v[112:115], v[182:185], v[198:201], v[112:115]
	v_mfma_f32_16x16x32_bf16 v[100:103], v[174:177], v[206:209], v[100:103]
	v_mfma_f32_16x16x32_bf16 v[96:99], v[182:185], v[206:209], v[96:99]
	v_mfma_f32_16x16x32_bf16 v[84:87], v[174:177], v[214:217], v[84:87]
	v_mfma_f32_16x16x32_bf16 v[80:83], v[182:185], v[214:217], v[80:83]
	v_mfma_f32_16x16x32_bf16 v[68:71], v[174:177], v[222:225], v[68:71]
	v_mfma_f32_16x16x32_bf16 v[64:67], v[182:185], v[222:225], v[64:67]
	s_setprio 0
	s_barrier
	s_add_i32 s59, s79, s69
	v_lshl_add_u64 v[158:159], s[8:9], 0, v[130:131]
	s_mov_b32 m0, s59
	ds_read_b128 v[194:197], v191 offset:16384
	ds_read_b128 v[198:201], v191 offset:17408
	ds_read_b128 v[202:205], v191 offset:18432
	ds_read_b128 v[206:209], v191 offset:19456
	ds_read_b128 v[210:213], v191 offset:20480
	ds_read_b128 v[214:217], v191 offset:21504
	ds_read_b128 v[218:221], v191 offset:22528
	ds_read_b128 v[222:225], v191 offset:23552
	global_load_lds_dwordx4 v[158:159], off
	s_add_i32 m0, s59, 0x2000
	s_add_u32 s60, s8, 0x80000
	v_lshl_add_u64 v[226:227], s[8:9], 0, v[134:135]
	s_addc_u32 s61, s9, 0
	s_add_i32 s59, s80, s69
	global_load_lds_dwordx4 v[226:227], off
	v_lshl_add_u64 v[228:229], s[60:61], 0, v[130:131]
	s_mov_b32 m0, s59
	v_lshl_add_u64 v[230:231], s[56:57], 0, v[132:133]
	global_load_lds_dwordx4 v[228:229], off
	v_lshl_add_u64 v[228:229], s[60:61], 0, v[134:135]
	s_add_i32 m0, s59, 0x2000
	s_nop 0
	global_load_lds_dwordx4 v[228:229], off
	v_lshl_add_u64 v[228:229], s[56:57], 0, v[128:129]
	s_mov_b32 m0, s70
	s_nop 0
	global_load_lds_dwordx4 v[228:229], off
	s_mov_b32 m0, s71
	s_nop 0
	global_load_lds_dwordx4 v[230:231], off
	s_cmp_eq_u32 s58, 28
	s_cbranch_scc1 .Lrstd_w1_last
	s_waitcnt vmcnt(8)
	s_branch .Lrstd_w1_done

.Lrstd_w1_done:
	s_waitcnt lgkmcnt(0)
	s_barrier
	s_setprio 1
	s_waitcnt lgkmcnt(0)
	v_mfma_f32_16x16x32_bf16 v[60:63], v[150:153], v[194:197], v[60:63]
	v_mfma_f32_16x16x32_bf16 v[56:59], v[162:165], v[194:197], v[56:59]
	v_mfma_f32_16x16x32_bf16 v[44:47], v[150:153], v[202:205], v[44:47]
	v_mfma_f32_16x16x32_bf16 v[40:43], v[162:165], v[202:205], v[40:43]
	v_mfma_f32_16x16x32_bf16 v[28:31], v[150:153], v[210:213], v[28:31]
	v_mfma_f32_16x16x32_bf16 v[24:27], v[162:165], v[210:213], v[24:27]
	v_mfma_f32_16x16x32_bf16 v[12:15], v[150:153], v[218:221], v[12:15]
	v_mfma_f32_16x16x32_bf16 v[8:11], v[162:165], v[218:221], v[8:11]
	v_mfma_f32_16x16x32_bf16 v[60:63], v[154:157], v[198:201], v[60:63]
	v_mfma_f32_16x16x32_bf16 v[56:59], v[166:169], v[198:201], v[56:59]
	v_mfma_f32_16x16x32_bf16 v[44:47], v[154:157], v[206:209], v[44:47]
	v_mfma_f32_16x16x32_bf16 v[40:43], v[166:169], v[206:209], v[40:43]
	v_mfma_f32_16x16x32_bf16 v[28:31], v[154:157], v[214:217], v[28:31]
	v_mfma_f32_16x16x32_bf16 v[24:27], v[166:169], v[214:217], v[24:27]
	v_mfma_f32_16x16x32_bf16 v[12:15], v[154:157], v[222:225], v[12:15]
	v_mfma_f32_16x16x32_bf16 v[8:11], v[166:169], v[222:225], v[8:11]
	s_setprio 0
	s_setprio 1
	v_mfma_f32_16x16x32_bf16 v[52:55], v[170:173], v[194:197], v[52:55]
	v_mfma_f32_16x16x32_bf16 v[48:51], v[178:181], v[194:197], v[48:51]
	v_mfma_f32_16x16x32_bf16 v[36:39], v[170:173], v[202:205], v[36:39]
	v_mfma_f32_16x16x32_bf16 v[32:35], v[178:181], v[202:205], v[32:35]
	v_mfma_f32_16x16x32_bf16 v[20:23], v[170:173], v[210:213], v[20:23]
	v_mfma_f32_16x16x32_bf16 v[16:19], v[178:181], v[210:213], v[16:19]
	v_mfma_f32_16x16x32_bf16 v[4:7], v[170:173], v[218:221], v[4:7]
	v_mfma_f32_16x16x32_bf16 v[0:3], v[178:181], v[218:221], v[0:3]
	v_mfma_f32_16x16x32_bf16 v[52:55], v[174:177], v[198:201], v[52:55]
	v_mfma_f32_16x16x32_bf16 v[48:51], v[182:185], v[198:201], v[48:51]
	v_mfma_f32_16x16x32_bf16 v[36:39], v[174:177], v[206:209], v[36:39]
	v_mfma_f32_16x16x32_bf16 v[32:35], v[182:185], v[206:209], v[32:35]
	v_mfma_f32_16x16x32_bf16 v[20:23], v[174:177], v[214:217], v[20:23]
	v_mfma_f32_16x16x32_bf16 v[16:19], v[182:185], v[214:217], v[16:19]
	v_mfma_f32_16x16x32_bf16 v[4:7], v[174:177], v[222:225], v[4:7]
	v_mfma_f32_16x16x32_bf16 v[0:3], v[182:185], v[222:225], v[0:3]
	s_setprio 0
	s_barrier
	s_add_i32 s59, 0, 0x18000
	s_add_i32 s60, 0, 0x1c000
	v_add_u32_e32 v166, s59, v187
	v_add_u32_e32 v182, s60, v187
	ds_read_b128 v[150:153], v166
	ds_read_b128 v[154:157], v166 offset:1024
	ds_read_b128 v[162:165], v166 offset:2048
	ds_read_b128 v[166:169], v166 offset:3072
	ds_read_b128 v[170:173], v182
	ds_read_b128 v[174:177], v182 offset:1024
	ds_read_b128 v[178:181], v182 offset:2048
	ds_read_b128 v[182:185], v182 offset:3072
	s_add_u32 s56, s56, 0x80000
	s_addc_u32 s57, s57, 0
	s_mov_b32 m0, s72
	v_lshl_add_u64 v[232:233], s[56:57], 0, v[128:129]
	ds_read_b128 v[194:197], v191 offset:32768
	ds_read_b128 v[198:201], v191 offset:33792
	ds_read_b128 v[202:205], v191 offset:34816
	ds_read_b128 v[206:209], v191 offset:35840
	ds_read_b128 v[210:213], v191 offset:36864
	ds_read_b128 v[214:217], v191 offset:37888
	ds_read_b128 v[218:221], v191 offset:38912
	ds_read_b128 v[222:225], v191 offset:39936
	global_load_lds_dwordx4 v[232:233], off
	v_lshl_add_u64 v[232:233], s[56:57], 0, v[132:133]
	s_mov_b32 m0, s73
	s_nop 0
	global_load_lds_dwordx4 v[232:233], off
	s_waitcnt vmcnt(8)
	s_waitcnt lgkmcnt(0)
	s_barrier
	s_setprio 1
	s_waitcnt lgkmcnt(0)
	v_mfma_f32_16x16x32_bf16 v[124:127], v[150:153], v[194:197], v[124:127]
	v_mfma_f32_16x16x32_bf16 v[120:123], v[162:165], v[194:197], v[120:123]
	v_mfma_f32_16x16x32_bf16 v[108:111], v[150:153], v[202:205], v[108:111]
	v_mfma_f32_16x16x32_bf16 v[104:107], v[162:165], v[202:205], v[104:107]
	v_mfma_f32_16x16x32_bf16 v[92:95], v[150:153], v[210:213], v[92:95]
	v_mfma_f32_16x16x32_bf16 v[88:91], v[162:165], v[210:213], v[88:91]
	v_mfma_f32_16x16x32_bf16 v[76:79], v[150:153], v[218:221], v[76:79]
	v_mfma_f32_16x16x32_bf16 v[72:75], v[162:165], v[218:221], v[72:75]
	v_mfma_f32_16x16x32_bf16 v[124:127], v[154:157], v[198:201], v[124:127]
	v_mfma_f32_16x16x32_bf16 v[120:123], v[166:169], v[198:201], v[120:123]
	v_mfma_f32_16x16x32_bf16 v[108:111], v[154:157], v[206:209], v[108:111]
	v_mfma_f32_16x16x32_bf16 v[104:107], v[166:169], v[206:209], v[104:107]
	v_mfma_f32_16x16x32_bf16 v[92:95], v[154:157], v[214:217], v[92:95]
	v_mfma_f32_16x16x32_bf16 v[88:91], v[166:169], v[214:217], v[88:91]
	v_mfma_f32_16x16x32_bf16 v[76:79], v[154:157], v[222:225], v[76:79]
	v_mfma_f32_16x16x32_bf16 v[72:75], v[166:169], v[222:225], v[72:75]
	s_setprio 0
	s_setprio 1
	v_mfma_f32_16x16x32_bf16 v[116:119], v[170:173], v[194:197], v[116:119]
	v_mfma_f32_16x16x32_bf16 v[112:115], v[178:181], v[194:197], v[112:115]
	v_mfma_f32_16x16x32_bf16 v[100:103], v[170:173], v[202:205], v[100:103]
	v_mfma_f32_16x16x32_bf16 v[96:99], v[178:181], v[202:205], v[96:99]
	v_mfma_f32_16x16x32_bf16 v[84:87], v[170:173], v[210:213], v[84:87]
	v_mfma_f32_16x16x32_bf16 v[80:83], v[178:181], v[210:213], v[80:83]
	v_mfma_f32_16x16x32_bf16 v[68:71], v[170:173], v[218:221], v[68:71]
	v_mfma_f32_16x16x32_bf16 v[64:67], v[178:181], v[218:221], v[64:67]
	v_mfma_f32_16x16x32_bf16 v[116:119], v[174:177], v[198:201], v[116:119]
	v_mfma_f32_16x16x32_bf16 v[112:115], v[182:185], v[198:201], v[112:115]
	v_mfma_f32_16x16x32_bf16 v[100:103], v[174:177], v[206:209], v[100:103]
	v_mfma_f32_16x16x32_bf16 v[96:99], v[182:185], v[206:209], v[96:99]
	v_mfma_f32_16x16x32_bf16 v[84:87], v[174:177], v[214:217], v[84:87]
	v_mfma_f32_16x16x32_bf16 v[80:83], v[182:185], v[214:217], v[80:83]
	v_mfma_f32_16x16x32_bf16 v[68:71], v[174:177], v[222:225], v[68:71]
	v_mfma_f32_16x16x32_bf16 v[64:67], v[182:185], v[222:225], v[64:67]
	s_setprio 0
	s_barrier
	s_add_i32 s56, s59, s69
	v_lshl_add_u64 v[158:159], v[158:159], 0, s[40:41]
	s_mov_b32 m0, s56
	ds_read_b128 v[194:197], v191 offset:49152
	ds_read_b128 v[198:201], v191 offset:50176
	ds_read_b128 v[202:205], v191 offset:51200
	ds_read_b128 v[206:209], v191 offset:52224
	ds_read_b128 v[210:213], v191 offset:53248
	ds_read_b128 v[214:217], v191 offset:54272
	ds_read_b128 v[218:221], v191 offset:55296
	ds_read_b128 v[222:225], v191 offset:56320
	global_load_lds_dwordx4 v[158:159], off
	s_add_i32 m0, s56, 0x2000
	s_add_u32 s8, s8, 0x80080
	v_lshl_add_u64 v[158:159], v[226:227], 0, s[40:41]
	s_addc_u32 s9, s9, 0
	s_add_i32 s56, s60, s69
	global_load_lds_dwordx4 v[158:159], off
	v_lshl_add_u64 v[158:159], s[8:9], 0, v[130:131]
	s_mov_b32 m0, s56
	s_nop 0
	global_load_lds_dwordx4 v[158:159], off
	v_lshl_add_u64 v[158:159], s[8:9], 0, v[134:135]
	s_add_i32 m0, s56, 0x2000
	s_nop 0
	global_load_lds_dwordx4 v[158:159], off
	v_lshl_add_u64 v[158:159], v[228:229], 0, s[40:41]
	s_mov_b32 m0, s76
	s_nop 0
	global_load_lds_dwordx4 v[158:159], off
	v_lshl_add_u64 v[158:159], v[230:231], 0, s[40:41]
	s_mov_b32 m0, s77
	s_nop 0
	global_load_lds_dwordx4 v[158:159], off
	s_waitcnt vmcnt(8)
	s_waitcnt lgkmcnt(0)
	s_barrier
	s_setprio 1
	s_waitcnt lgkmcnt(0)
	v_mfma_f32_16x16x32_bf16 v[60:63], v[150:153], v[194:197], v[60:63]
	v_mfma_f32_16x16x32_bf16 v[56:59], v[162:165], v[194:197], v[56:59]
	v_mfma_f32_16x16x32_bf16 v[44:47], v[150:153], v[202:205], v[44:47]
	v_mfma_f32_16x16x32_bf16 v[40:43], v[162:165], v[202:205], v[40:43]
	v_mfma_f32_16x16x32_bf16 v[28:31], v[150:153], v[210:213], v[28:31]
	v_mfma_f32_16x16x32_bf16 v[24:27], v[162:165], v[210:213], v[24:27]
	v_mfma_f32_16x16x32_bf16 v[12:15], v[150:153], v[218:221], v[12:15]
	v_mfma_f32_16x16x32_bf16 v[8:11], v[162:165], v[218:221], v[8:11]
	v_mfma_f32_16x16x32_bf16 v[60:63], v[154:157], v[198:201], v[60:63]
	v_mfma_f32_16x16x32_bf16 v[56:59], v[166:169], v[198:201], v[56:59]
	v_mfma_f32_16x16x32_bf16 v[44:47], v[154:157], v[206:209], v[44:47]
	v_mfma_f32_16x16x32_bf16 v[40:43], v[166:169], v[206:209], v[40:43]
	v_mfma_f32_16x16x32_bf16 v[28:31], v[154:157], v[214:217], v[28:31]
	v_mfma_f32_16x16x32_bf16 v[24:27], v[166:169], v[214:217], v[24:27]
	v_mfma_f32_16x16x32_bf16 v[12:15], v[154:157], v[222:225], v[12:15]
	v_mfma_f32_16x16x32_bf16 v[8:11], v[166:169], v[222:225], v[8:11]
	s_setprio 0
	s_setprio 1
	v_mfma_f32_16x16x32_bf16 v[52:55], v[170:173], v[194:197], v[52:55]
	v_mfma_f32_16x16x32_bf16 v[48:51], v[178:181], v[194:197], v[48:51]
	v_mfma_f32_16x16x32_bf16 v[36:39], v[170:173], v[202:205], v[36:39]
	v_mfma_f32_16x16x32_bf16 v[32:35], v[178:181], v[202:205], v[32:35]
	v_mfma_f32_16x16x32_bf16 v[20:23], v[170:173], v[210:213], v[20:23]
	v_mfma_f32_16x16x32_bf16 v[16:19], v[178:181], v[210:213], v[16:19]
	v_mfma_f32_16x16x32_bf16 v[4:7], v[170:173], v[218:221], v[4:7]
	v_mfma_f32_16x16x32_bf16 v[0:3], v[178:181], v[218:221], v[0:3]
	v_mfma_f32_16x16x32_bf16 v[52:55], v[174:177], v[198:201], v[52:55]
	v_mfma_f32_16x16x32_bf16 v[48:51], v[182:185], v[198:201], v[48:51]
	v_mfma_f32_16x16x32_bf16 v[36:39], v[174:177], v[206:209], v[36:39]
	v_mfma_f32_16x16x32_bf16 v[32:35], v[182:185], v[206:209], v[32:35]
	v_mfma_f32_16x16x32_bf16 v[20:23], v[174:177], v[214:217], v[20:23]
	v_mfma_f32_16x16x32_bf16 v[16:19], v[182:185], v[214:217], v[16:19]
	v_mfma_f32_16x16x32_bf16 v[4:7], v[174:177], v[222:225], v[4:7]
	v_mfma_f32_16x16x32_bf16 v[0:3], v[182:185], v[222:225], v[0:3]
	s_setprio 0
	s_barrier
	s_add_i32 s58, s58, 2
	s_add_u32 s2, s2, 0x100
	s_addc_u32 s3, s3, 0
	s_add_u32 s49, s49, 0x100
	s_addc_u32 s51, s51, 0
	s_cmp_gt_u32 s58, 29
	s_cbranch_scc0 .LBB0_218
	s_and_b64 vcc, exec, s[42:43]
	s_cbranch_vccz .LBB0_222
	s_barrier
	v_lshl_add_u32 v150, s0, 8, v186
	s_cmp_lg_u32 s6, 25
	s_mov_b64 s[0:1], -1
	s_cbranch_scc1 .LBB0_223

.LBB0_241:
	v_ashrrev_i32_e32 v151, 31, v150
	v_lshl_add_u64 v[154:155], v[150:151], 2, s[66:67]
	v_cndmask_b32_e64 v153, 0, 1, s[60:61]
	v_cmp_ne_u32_e64 s[6:7], 1, v153
	s_andn2_b64 vcc, exec, s[60:61]
	s_waitcnt vmcnt(0)
	v_mov_b32_e32 v152, v234
	v_mul_f32_e32 v153, 0x3e0293ee, v152
	v_cndmask_b32_e64 v170, v152, v153, s[56:57]
	v_pk_mul_f32 v[162:163], v[126:127], v[170:171] op_sel_hi:[1,0]
	v_pk_mul_f32 v[164:165], v[124:125], v[170:171] op_sel_hi:[1,0]
	v_pk_mul_f32 v[156:157], v[122:123], v[170:171] op_sel_hi:[1,0]
	v_pk_mul_f32 v[158:159], v[120:121], v[170:171] op_sel_hi:[1,0]
	v_mov_b32_e32 v166, v164
	v_mov_b32_e32 v167, v165
	v_mov_b32_e32 v172, v162
	v_mov_b32_e32 v173, v163
	v_mov_b32_e32 v168, v158
	v_mov_b32_e32 v169, v159
	v_mov_b32_e32 v176, v156
	v_mov_b32_e32 v177, v157
	s_cbranch_vccnz .LBB0_243
	v_mul_f32_e32 v153, 0xbfb8aa3b, v158
	v_exp_f32_e32 v153, v153
	v_mul_f32_e32 v166, 0xbfb8aa3b, v165
	v_mul_f32_e32 v167, 0xbfb8aa3b, v159
	v_exp_f32_e32 v166, v166
	v_exp_f32_e32 v167, v167
	v_add_f32_e32 v153, 1.0, v153
	v_rcp_f32_e32 v168, v153
	v_add_f32_e32 v153, 1.0, v166
	v_add_f32_e32 v166, 1.0, v167
	v_mul_f32_e32 v167, 0xbfb8aa3b, v162
	v_exp_f32_e32 v167, v167
	v_mul_f32_e32 v169, 0xbfb8aa3b, v156
	v_exp_f32_e32 v171, v169
	v_rcp_f32_e32 v169, v166
	v_add_f32_e32 v166, 1.0, v167
	v_mul_f32_e32 v167, 0xbfb8aa3b, v163
	v_mul_f32_e32 v152, 0xbfb8aa3b, v164
	v_rcp_f32_e32 v172, v166
	v_add_f32_e32 v166, 1.0, v171
	v_exp_f32_e32 v167, v167
	v_mul_f32_e32 v171, 0xbfb8aa3b, v157
	v_exp_f32_e32 v152, v152
	v_exp_f32_e32 v171, v171
	v_rcp_f32_e32 v174, v166
	v_add_f32_e32 v166, 1.0, v167
	v_add_f32_e32 v152, 1.0, v152
	v_rcp_f32_e32 v173, v166
	v_add_f32_e32 v166, 1.0, v171
	v_rcp_f32_e32 v152, v152
	v_rcp_f32_e32 v153, v153
	v_rcp_f32_e32 v175, v166
	v_pk_mul_f32 v[168:169], v[158:159], v[168:169]
	v_pk_mul_f32 v[172:173], v[162:163], v[172:173]
	v_pk_mul_f32 v[166:167], v[164:165], v[152:153]
	v_pk_mul_f32 v[176:177], v[156:157], v[174:175]

.LBB0_249:
	v_mov_b32_e32 v151, v235
	s_and_b64 vcc, exec, s[6:7]
	s_nop 0
	v_mul_f32_e32 v156, 0x3e0293ee, v151
	v_cndmask_b32_e64 v172, v151, v156, s[56:57]
	v_pk_mul_f32 v[162:163], v[110:111], v[172:173] op_sel_hi:[1,0]
	v_pk_mul_f32 v[164:165], v[108:109], v[172:173] op_sel_hi:[1,0]
	s_waitcnt lgkmcnt(0)
	v_pk_mul_f32 v[156:157], v[106:107], v[172:173] op_sel_hi:[1,0]
	v_pk_mul_f32 v[158:159], v[104:105], v[172:173] op_sel_hi:[1,0]
	v_mov_b32_e32 v168, v164
	v_mov_b32_e32 v169, v165
	v_mov_b32_e32 v174, v162
	v_mov_b32_e32 v175, v163
	v_mov_b32_e32 v170, v158
	v_mov_b32_e32 v171, v159
	v_mov_b32_e32 v178, v156
	v_mov_b32_e32 v179, v157
	s_cbranch_vccnz .LBB0_251
	v_mul_f32_e32 v151, 0xbfb8aa3b, v164
	v_exp_f32_e32 v151, v151
	v_mul_f32_e32 v166, 0xbfb8aa3b, v158
	v_exp_f32_e32 v166, v166
	v_mul_f32_e32 v168, 0xbfb8aa3b, v159
	v_add_f32_e32 v151, 1.0, v151
	v_exp_f32_e32 v168, v168
	v_add_f32_e32 v167, 1.0, v166
	v_rcp_f32_e32 v166, v151
	v_mul_f32_e32 v151, 0xbfb8aa3b, v165
	v_exp_f32_e32 v151, v151
	v_rcp_f32_e32 v170, v167
	v_mul_f32_e32 v169, 0xbfb8aa3b, v156
	v_exp_f32_e32 v169, v169
	v_add_f32_e32 v151, 1.0, v151
	v_rcp_f32_e32 v167, v151
	v_add_f32_e32 v151, 1.0, v168
	v_mul_f32_e32 v168, 0xbfb8aa3b, v162
	v_exp_f32_e32 v168, v168
	v_rcp_f32_e32 v171, v151
	v_add_f32_e32 v151, 1.0, v168
	v_mul_f32_e32 v168, 0xbfb8aa3b, v163
	v_rcp_f32_e32 v174, v151
	v_add_f32_e32 v151, 1.0, v169
	v_exp_f32_e32 v168, v168
	v_mul_f32_e32 v169, 0xbfb8aa3b, v157
	v_exp_f32_e32 v169, v169
	v_rcp_f32_e32 v176, v151
	v_add_f32_e32 v151, 1.0, v168
	v_rcp_f32_e32 v175, v151
	v_add_f32_e32 v151, 1.0, v169
	v_rcp_f32_e32 v177, v151
	v_pk_mul_f32 v[168:169], v[164:165], v[166:167]
	v_pk_mul_f32 v[170:171], v[158:159], v[170:171]
	v_pk_mul_f32 v[174:175], v[162:163], v[174:175]
	v_pk_mul_f32 v[178:179], v[156:157], v[176:177]

.LBB0_257:
	v_mov_b32_e32 v151, v236
	s_and_b64 vcc, exec, s[6:7]
	s_nop 0
	v_mul_f32_e32 v156, 0x3e0293ee, v151
	v_cndmask_b32_e64 v172, v151, v156, s[56:57]
	v_pk_mul_f32 v[162:163], v[94:95], v[172:173] op_sel_hi:[1,0]
	v_pk_mul_f32 v[164:165], v[92:93], v[172:173] op_sel_hi:[1,0]
	s_waitcnt lgkmcnt(0)
	v_pk_mul_f32 v[156:157], v[90:91], v[172:173] op_sel_hi:[1,0]
	v_pk_mul_f32 v[158:159], v[88:89], v[172:173] op_sel_hi:[1,0]
	v_mov_b32_e32 v168, v164
	v_mov_b32_e32 v169, v165
	v_mov_b32_e32 v174, v162
	v_mov_b32_e32 v175, v163
	v_mov_b32_e32 v170, v158
	v_mov_b32_e32 v171, v159
	v_mov_b32_e32 v178, v156
	v_mov_b32_e32 v179, v157
	s_cbranch_vccnz .LBB0_259
	v_mul_f32_e32 v151, 0xbfb8aa3b, v164
	v_exp_f32_e32 v151, v151
	v_mul_f32_e32 v166, 0xbfb8aa3b, v158
	v_exp_f32_e32 v166, v166
	v_mul_f32_e32 v168, 0xbfb8aa3b, v159
	v_add_f32_e32 v151, 1.0, v151
	v_exp_f32_e32 v168, v168
	v_add_f32_e32 v167, 1.0, v166
	v_rcp_f32_e32 v166, v151
	v_mul_f32_e32 v151, 0xbfb8aa3b, v165
	v_exp_f32_e32 v151, v151
	v_rcp_f32_e32 v170, v167
	v_mul_f32_e32 v169, 0xbfb8aa3b, v156
	v_exp_f32_e32 v169, v169
	v_add_f32_e32 v151, 1.0, v151
	v_rcp_f32_e32 v167, v151
	v_add_f32_e32 v151, 1.0, v168
	v_mul_f32_e32 v168, 0xbfb8aa3b, v162
	v_exp_f32_e32 v168, v168
	v_rcp_f32_e32 v171, v151
	v_add_f32_e32 v151, 1.0, v168
	v_mul_f32_e32 v168, 0xbfb8aa3b, v163
	v_rcp_f32_e32 v174, v151
	v_add_f32_e32 v151, 1.0, v169
	v_exp_f32_e32 v168, v168
	v_mul_f32_e32 v169, 0xbfb8aa3b, v157
	v_exp_f32_e32 v169, v169
	v_rcp_f32_e32 v176, v151
	v_add_f32_e32 v151, 1.0, v168
	v_rcp_f32_e32 v175, v151
	v_add_f32_e32 v151, 1.0, v169
	v_rcp_f32_e32 v177, v151
	v_pk_mul_f32 v[168:169], v[164:165], v[166:167]
	v_pk_mul_f32 v[170:171], v[158:159], v[170:171]
	v_pk_mul_f32 v[174:175], v[162:163], v[174:175]
	v_pk_mul_f32 v[178:179], v[156:157], v[176:177]

.LBB0_265:
	v_mov_b32_e32 v151, v237
	s_and_b64 vcc, exec, s[6:7]
	s_nop 0
	v_mul_f32_e32 v156, 0x3e0293ee, v151
	v_cndmask_b32_e64 v172, v151, v156, s[56:57]
	v_pk_mul_f32 v[162:163], v[78:79], v[172:173] op_sel_hi:[1,0]
	v_pk_mul_f32 v[164:165], v[76:77], v[172:173] op_sel_hi:[1,0]
	s_waitcnt lgkmcnt(0)
	v_pk_mul_f32 v[156:157], v[74:75], v[172:173] op_sel_hi:[1,0]
	v_pk_mul_f32 v[158:159], v[72:73], v[172:173] op_sel_hi:[1,0]
	v_mov_b32_e32 v168, v164
	v_mov_b32_e32 v169, v165
	v_mov_b32_e32 v174, v162
	v_mov_b32_e32 v175, v163
	v_mov_b32_e32 v170, v158
	v_mov_b32_e32 v171, v159
	v_mov_b32_e32 v178, v156
	v_mov_b32_e32 v179, v157
	s_cbranch_vccnz .LBB0_267
	v_mul_f32_e32 v151, 0xbfb8aa3b, v164
	v_exp_f32_e32 v151, v151
	v_mul_f32_e32 v166, 0xbfb8aa3b, v158
	v_exp_f32_e32 v166, v166
	v_mul_f32_e32 v168, 0xbfb8aa3b, v159
	v_add_f32_e32 v151, 1.0, v151
	v_exp_f32_e32 v168, v168
	v_add_f32_e32 v167, 1.0, v166
	v_rcp_f32_e32 v166, v151
	v_mul_f32_e32 v151, 0xbfb8aa3b, v165
	v_exp_f32_e32 v151, v151
	v_rcp_f32_e32 v170, v167
	v_mul_f32_e32 v169, 0xbfb8aa3b, v156
	v_exp_f32_e32 v169, v169
	v_add_f32_e32 v151, 1.0, v151
	v_rcp_f32_e32 v167, v151
	v_add_f32_e32 v151, 1.0, v168
	v_mul_f32_e32 v168, 0xbfb8aa3b, v162
	v_exp_f32_e32 v168, v168
	v_rcp_f32_e32 v171, v151
	v_add_f32_e32 v151, 1.0, v168
	v_mul_f32_e32 v168, 0xbfb8aa3b, v163
	v_rcp_f32_e32 v174, v151
	v_add_f32_e32 v151, 1.0, v169
	v_exp_f32_e32 v168, v168
	v_mul_f32_e32 v169, 0xbfb8aa3b, v157
	v_exp_f32_e32 v169, v169
	v_rcp_f32_e32 v176, v151
	v_add_f32_e32 v151, 1.0, v168
	v_rcp_f32_e32 v175, v151
	v_add_f32_e32 v151, 1.0, v169
	v_rcp_f32_e32 v177, v151
	v_pk_mul_f32 v[168:169], v[164:165], v[166:167]
	v_pk_mul_f32 v[170:171], v[158:159], v[170:171]
	v_pk_mul_f32 v[174:175], v[162:163], v[174:175]
	v_pk_mul_f32 v[178:179], v[156:157], v[176:177]

.LBB0_273:
	v_mov_b32_e32 v151, v238
	s_and_b64 vcc, exec, s[6:7]
	s_nop 0
	v_mul_f32_e32 v156, 0x3e0293ee, v151
	v_cndmask_b32_e64 v172, v151, v156, s[56:57]
	v_pk_mul_f32 v[162:163], v[62:63], v[172:173] op_sel_hi:[1,0]
	v_pk_mul_f32 v[164:165], v[60:61], v[172:173] op_sel_hi:[1,0]
	s_waitcnt lgkmcnt(0)
	v_pk_mul_f32 v[156:157], v[58:59], v[172:173] op_sel_hi:[1,0]
	v_pk_mul_f32 v[158:159], v[56:57], v[172:173] op_sel_hi:[1,0]
	v_mov_b32_e32 v168, v164
	v_mov_b32_e32 v169, v165
	v_mov_b32_e32 v174, v162
	v_mov_b32_e32 v175, v163
	v_mov_b32_e32 v170, v158
	v_mov_b32_e32 v171, v159
	v_mov_b32_e32 v178, v156
	v_mov_b32_e32 v179, v157
	s_cbranch_vccnz .LBB0_275
	v_mul_f32_e32 v151, 0xbfb8aa3b, v164
	v_exp_f32_e32 v151, v151
	v_mul_f32_e32 v166, 0xbfb8aa3b, v158
	v_exp_f32_e32 v166, v166
	v_mul_f32_e32 v168, 0xbfb8aa3b, v159
	v_add_f32_e32 v151, 1.0, v151
	v_exp_f32_e32 v168, v168
	v_add_f32_e32 v167, 1.0, v166
	v_rcp_f32_e32 v166, v151
	v_mul_f32_e32 v151, 0xbfb8aa3b, v165
	v_exp_f32_e32 v151, v151
	v_rcp_f32_e32 v170, v167
	v_mul_f32_e32 v169, 0xbfb8aa3b, v156
	v_exp_f32_e32 v169, v169
	v_add_f32_e32 v151, 1.0, v151
	v_rcp_f32_e32 v167, v151
	v_add_f32_e32 v151, 1.0, v168
	v_mul_f32_e32 v168, 0xbfb8aa3b, v162
	v_exp_f32_e32 v168, v168
	v_rcp_f32_e32 v171, v151
	v_add_f32_e32 v151, 1.0, v168
	v_mul_f32_e32 v168, 0xbfb8aa3b, v163
	v_rcp_f32_e32 v174, v151
	v_add_f32_e32 v151, 1.0, v169
	v_exp_f32_e32 v168, v168
	v_mul_f32_e32 v169, 0xbfb8aa3b, v157
	v_exp_f32_e32 v169, v169
	v_rcp_f32_e32 v176, v151
	v_add_f32_e32 v151, 1.0, v168
	v_rcp_f32_e32 v175, v151
	v_add_f32_e32 v151, 1.0, v169
	v_rcp_f32_e32 v177, v151
	v_pk_mul_f32 v[168:169], v[164:165], v[166:167]
	v_pk_mul_f32 v[170:171], v[158:159], v[170:171]
	v_pk_mul_f32 v[174:175], v[162:163], v[174:175]
	v_pk_mul_f32 v[178:179], v[156:157], v[176:177]

.LBB0_281:
	v_mov_b32_e32 v151, v239
	s_and_b64 vcc, exec, s[6:7]
	s_nop 0
	v_mul_f32_e32 v156, 0x3e0293ee, v151
	v_cndmask_b32_e64 v172, v151, v156, s[56:57]
	v_pk_mul_f32 v[162:163], v[46:47], v[172:173] op_sel_hi:[1,0]
	v_pk_mul_f32 v[164:165], v[44:45], v[172:173] op_sel_hi:[1,0]
	s_waitcnt lgkmcnt(0)
	v_pk_mul_f32 v[156:157], v[42:43], v[172:173] op_sel_hi:[1,0]
	v_pk_mul_f32 v[158:159], v[40:41], v[172:173] op_sel_hi:[1,0]
	v_mov_b32_e32 v168, v164
	v_mov_b32_e32 v169, v165
	v_mov_b32_e32 v174, v162
	v_mov_b32_e32 v175, v163
	v_mov_b32_e32 v170, v158
	v_mov_b32_e32 v171, v159
	v_mov_b32_e32 v178, v156
	v_mov_b32_e32 v179, v157
	s_cbranch_vccnz .LBB0_283
	v_mul_f32_e32 v151, 0xbfb8aa3b, v164
	v_exp_f32_e32 v151, v151
	v_mul_f32_e32 v166, 0xbfb8aa3b, v158
	v_exp_f32_e32 v166, v166
	v_mul_f32_e32 v168, 0xbfb8aa3b, v159
	v_add_f32_e32 v151, 1.0, v151
	v_exp_f32_e32 v168, v168
	v_add_f32_e32 v167, 1.0, v166
	v_rcp_f32_e32 v166, v151
	v_mul_f32_e32 v151, 0xbfb8aa3b, v165
	v_exp_f32_e32 v151, v151
	v_rcp_f32_e32 v170, v167
	v_mul_f32_e32 v169, 0xbfb8aa3b, v156
	v_exp_f32_e32 v169, v169
	v_add_f32_e32 v151, 1.0, v151
	v_rcp_f32_e32 v167, v151
	v_add_f32_e32 v151, 1.0, v168
	v_mul_f32_e32 v168, 0xbfb8aa3b, v162
	v_exp_f32_e32 v168, v168
	v_rcp_f32_e32 v171, v151
	v_add_f32_e32 v151, 1.0, v168
	v_mul_f32_e32 v168, 0xbfb8aa3b, v163
	v_rcp_f32_e32 v174, v151
	v_add_f32_e32 v151, 1.0, v169
	v_exp_f32_e32 v168, v168
	v_mul_f32_e32 v169, 0xbfb8aa3b, v157
	v_exp_f32_e32 v169, v169
	v_rcp_f32_e32 v176, v151
	v_add_f32_e32 v151, 1.0, v168
	v_rcp_f32_e32 v175, v151
	v_add_f32_e32 v151, 1.0, v169
	v_rcp_f32_e32 v177, v151
	v_pk_mul_f32 v[168:169], v[164:165], v[166:167]
	v_pk_mul_f32 v[170:171], v[158:159], v[170:171]
	v_pk_mul_f32 v[174:175], v[162:163], v[174:175]
	v_pk_mul_f32 v[178:179], v[156:157], v[176:177]

.LBB0_289:
	v_mov_b32_e32 v151, v240
	s_and_b64 vcc, exec, s[6:7]
	s_nop 0
	v_mul_f32_e32 v156, 0x3e0293ee, v151
	v_cndmask_b32_e64 v172, v151, v156, s[56:57]
	v_pk_mul_f32 v[162:163], v[30:31], v[172:173] op_sel_hi:[1,0]
	v_pk_mul_f32 v[164:165], v[28:29], v[172:173] op_sel_hi:[1,0]
	s_waitcnt lgkmcnt(0)
	v_pk_mul_f32 v[156:157], v[26:27], v[172:173] op_sel_hi:[1,0]
	v_pk_mul_f32 v[158:159], v[24:25], v[172:173] op_sel_hi:[1,0]
	v_mov_b32_e32 v168, v164
	v_mov_b32_e32 v169, v165
	v_mov_b32_e32 v174, v162
	v_mov_b32_e32 v175, v163
	v_mov_b32_e32 v170, v158
	v_mov_b32_e32 v171, v159
	v_mov_b32_e32 v178, v156
	v_mov_b32_e32 v179, v157
	s_cbranch_vccnz .LBB0_291
	v_mul_f32_e32 v151, 0xbfb8aa3b, v164
	v_exp_f32_e32 v151, v151
	v_mul_f32_e32 v166, 0xbfb8aa3b, v158
	v_exp_f32_e32 v166, v166
	v_mul_f32_e32 v168, 0xbfb8aa3b, v159
	v_add_f32_e32 v151, 1.0, v151
	v_exp_f32_e32 v168, v168
	v_add_f32_e32 v167, 1.0, v166
	v_rcp_f32_e32 v166, v151
	v_mul_f32_e32 v151, 0xbfb8aa3b, v165
	v_exp_f32_e32 v151, v151
	v_rcp_f32_e32 v170, v167
	v_mul_f32_e32 v169, 0xbfb8aa3b, v156
	v_exp_f32_e32 v169, v169
	v_add_f32_e32 v151, 1.0, v151
	v_rcp_f32_e32 v167, v151
	v_add_f32_e32 v151, 1.0, v168
	v_mul_f32_e32 v168, 0xbfb8aa3b, v162
	v_exp_f32_e32 v168, v168
	v_rcp_f32_e32 v171, v151
	v_add_f32_e32 v151, 1.0, v168
	v_mul_f32_e32 v168, 0xbfb8aa3b, v163
	v_rcp_f32_e32 v174, v151
	v_add_f32_e32 v151, 1.0, v169
	v_exp_f32_e32 v168, v168
	v_mul_f32_e32 v169, 0xbfb8aa3b, v157
	v_exp_f32_e32 v169, v169
	v_rcp_f32_e32 v176, v151
	v_add_f32_e32 v151, 1.0, v168
	v_rcp_f32_e32 v175, v151
	v_add_f32_e32 v151, 1.0, v169
	v_rcp_f32_e32 v177, v151
	v_pk_mul_f32 v[168:169], v[164:165], v[166:167]
	v_pk_mul_f32 v[170:171], v[158:159], v[170:171]
	v_pk_mul_f32 v[174:175], v[162:163], v[174:175]
	v_pk_mul_f32 v[178:179], v[156:157], v[176:177]

.LBB0_297:
	v_mov_b32_e32 v151, v241
	s_and_b64 vcc, exec, s[6:7]
	s_nop 0
	v_mul_f32_e32 v154, 0x3e0293ee, v151
	v_cndmask_b32_e64 v168, v151, v154, s[56:57]
	v_pk_mul_f32 v[158:159], v[14:15], v[168:169] op_sel_hi:[1,0]
	v_pk_mul_f32 v[162:163], v[12:13], v[168:169] op_sel_hi:[1,0]
	v_pk_mul_f32 v[154:155], v[10:11], v[168:169] op_sel_hi:[1,0]
	s_waitcnt lgkmcnt(0)
	v_pk_mul_f32 v[156:157], v[8:9], v[168:169] op_sel_hi:[1,0]
	v_mov_b32_e32 v166, v162
	v_mov_b32_e32 v167, v163
	v_mov_b32_e32 v174, v158
	v_mov_b32_e32 v175, v159
	v_mov_b32_e32 v170, v156
	v_mov_b32_e32 v171, v157
	v_mov_b32_e32 v176, v154
	v_mov_b32_e32 v177, v155
	s_cbranch_vccnz .LBB0_299
	v_mul_f32_e32 v151, 0xbfb8aa3b, v162
	v_exp_f32_e32 v151, v151
	v_mul_f32_e32 v164, 0xbfb8aa3b, v156
	v_exp_f32_e32 v164, v164
	v_mul_f32_e32 v166, 0xbfb8aa3b, v157
	v_add_f32_e32 v151, 1.0, v151
	v_exp_f32_e32 v166, v166
	v_add_f32_e32 v165, 1.0, v164
	v_rcp_f32_e32 v164, v151
	v_mul_f32_e32 v151, 0xbfb8aa3b, v163
	v_exp_f32_e32 v151, v151
	v_rcp_f32_e32 v170, v165
	v_mul_f32_e32 v167, 0xbfb8aa3b, v154
	v_exp_f32_e32 v167, v167
	v_add_f32_e32 v151, 1.0, v151
	v_rcp_f32_e32 v165, v151
	v_add_f32_e32 v151, 1.0, v166
	v_mul_f32_e32 v166, 0xbfb8aa3b, v158
	v_exp_f32_e32 v166, v166
	v_rcp_f32_e32 v171, v151
	v_add_f32_e32 v151, 1.0, v166
	v_mul_f32_e32 v166, 0xbfb8aa3b, v159
	v_rcp_f32_e32 v172, v151
	v_add_f32_e32 v151, 1.0, v167
	v_exp_f32_e32 v166, v166
	v_mul_f32_e32 v167, 0xbfb8aa3b, v155
	v_exp_f32_e32 v167, v167
	v_rcp_f32_e32 v176, v151
	v_add_f32_e32 v151, 1.0, v166
	v_rcp_f32_e32 v173, v151
	v_add_f32_e32 v151, 1.0, v167
	v_rcp_f32_e32 v177, v151
	v_pk_mul_f32 v[166:167], v[162:163], v[164:165]
	v_pk_mul_f32 v[170:171], v[156:157], v[170:171]
	v_pk_mul_f32 v[174:175], v[158:159], v[172:173]
	v_pk_mul_f32 v[176:177], v[154:155], v[176:177]
